# setup adaLN k-loop: two 8-row groups per trip (16 loads in flight); final-norm loop and conv tile no longer wait for the previous tile's stores before loading
# speedup vs baseline: 1.0066x; 1.0066x over previous
; __device__ __forceinline__ void phase_final(const Params& p) {
;     ...
;   for (int t = blockIdx.x; t < 16384 / 4; t += gridDim.x) {
;     int r = t * 4 + w;
;     float* src = p.out + (size_t)r * 1024;
;     float4 v[4];
;     float ss = 0;
; #pragma unroll
;     for (int i = 0; i < 4; ++i) {
;       v[i] = *(const float4*)(src + lane * 4 + 256 * i);
;       ss += v[i].x * v[i].x + v[i].y * v[i].y + v[i].z * v[i].z + v[i].w * v[i].w;
;     }
;     ss = sum64(ss);
;     float rstd = rsqrtf(ss * (1.f / 1024.f) + 1e-6f);
; #pragma unroll
;     for (int i = 0; i < 4; ++i) {
;       int k = lane * 4 + 256 * i;
;       float4 n4 = *(const float4*)(p.final_norm_w + k);
;       float4 o;
;       o.x = v[i].x * rstd * n4.x; o.y = v[i].y * rstd * n4.y; o.z = v[i].z * rstd * n4.z; o.w = v[i].w * rstd * n4.w;
;       *(float4*)(src + k) = o;
;     }
.LBB0_77:
	v_ashrrev_i32_e32 v5, 31, v4
	v_lshlrev_b64 v[12:13], 12, v[4:5]
	s_nop 0
	v_lshl_add_u64 v[32:33], v[2:3], 0, v[12:13]
	global_load_dwordx4 v[12:15], v[32:33], off
	global_load_dwordx4 v[16:19], v[32:33], off offset:1024
	global_load_dwordx4 v[20:23], v[32:33], off offset:2048
	global_load_dwordx4 v[24:27], v[32:33], off offset:3072
	s_add_i32 s45, s45, s28
	s_cmpk_gt_i32 s45, 0xfff
	v_add_u32_e32 v4, s44, v4
	s_waitcnt vmcnt(3)
	v_mov_b32_e32 v36, v13
	s_waitcnt vmcnt(2)
	v_mov_b32_e32 v37, v17
	v_mov_b32_e32 v34, v12
	v_mov_b32_e32 v35, v16
	s_waitcnt vmcnt(1)
	v_mov_b32_e32 v44, v21
	s_waitcnt vmcnt(0)
	v_mov_b32_e32 v45, v25
	v_pk_mul_f32 v[36:37], v[36:37], v[36:37]
	v_mov_b32_e32 v38, v14
	v_mov_b32_e32 v39, v18
	v_mov_b32_e32 v42, v20
	v_mov_b32_e32 v43, v24
	v_pk_mul_f32 v[44:45], v[44:45], v[44:45]
	v_pk_fma_f32 v[34:35], v[34:35], v[34:35], v[36:37]
	v_mov_b32_e32 v40, v15
	v_mov_b32_e32 v41, v19
	v_mov_b32_e32 v46, v22
	v_mov_b32_e32 v47, v26
	v_pk_fma_f32 v[36:37], v[42:43], v[42:43], v[44:45]
	v_pk_fma_f32 v[34:35], v[38:39], v[38:39], v[34:35]
	v_mov_b32_e32 v48, v23
	v_mov_b32_e32 v49, v27
	v_pk_fma_f32 v[36:37], v[46:47], v[46:47], v[36:37]
	v_pk_fma_f32 v[34:35], v[40:41], v[40:41], v[34:35]
	v_pk_fma_f32 v[36:37], v[48:49], v[48:49], v[36:37]
	v_add_f32_e32 v5, v34, v35
	v_add_f32_e32 v5, v5, v36
	v_add_f32_e32 v5, v5, v37
	ds_bpermute_b32 v34, v6, v5
	s_waitcnt lgkmcnt(0)
	v_add_f32_e32 v5, v5, v34
	ds_bpermute_b32 v34, v7, v5
	s_waitcnt lgkmcnt(0)
	v_add_f32_e32 v5, v5, v34
	ds_bpermute_b32 v34, v8, v5
	s_waitcnt lgkmcnt(0)
	v_add_f32_e32 v5, v5, v34
	ds_bpermute_b32 v34, v9, v5
	s_waitcnt lgkmcnt(0)
	v_add_f32_e32 v5, v5, v34
	ds_bpermute_b32 v34, v10, v5
	s_waitcnt lgkmcnt(0)
	v_add_f32_e32 v5, v5, v34
	ds_bpermute_b32 v34, v11, v5
	s_waitcnt lgkmcnt(0)
	v_add_f32_e32 v5, v5, v34
	v_fmamk_f32 v5, v5, 0x3a800000, v191
	v_mul_f32_e32 v34, 0x4b800000, v5
	v_cmp_gt_f32_e32 vcc, s46, v5
	s_nop 1
	v_cndmask_b32_e32 v5, v5, v34, vcc
	v_rsq_f32_e32 v5, v5
	s_nop 0
	v_mul_f32_e32 v34, 0x45800000, v5
	v_cndmask_b32_e32 v34, v5, v34, vcc
	v_pk_mul_f32 v[12:13], v[12:13], v[34:35] op_sel_hi:[1,0]
	v_pk_mul_f32 v[14:15], v[14:15], v[34:35] op_sel_hi:[1,0]
	s_waitcnt vmcnt(0)
	v_pk_mul_f32 v[12:13], v[50:51], v[12:13]
	v_pk_mul_f32 v[14:15], v[52:53], v[14:15]
	global_store_dwordx4 v[32:33], v[12:15], off
	s_nop 0
	v_pk_mul_f32 v[16:17], v[16:17], v[34:35] op_sel_hi:[1,0]
	v_pk_mul_f32 v[18:19], v[18:19], v[34:35] op_sel_hi:[1,0]
	v_pk_mul_f32 v[12:13], v[16:17], v[54:55]
	v_pk_mul_f32 v[14:15], v[18:19], v[56:57]
	global_store_dwordx4 v[32:33], v[12:15], off offset:1024
	s_nop 0
	v_pk_mul_f32 v[16:17], v[20:21], v[34:35] op_sel_hi:[1,0]
	v_pk_mul_f32 v[18:19], v[22:23], v[34:35] op_sel_hi:[1,0]
	v_pk_mul_f32 v[12:13], v[16:17], v[58:59]
	v_pk_mul_f32 v[14:15], v[18:19], v[60:61]
	global_store_dwordx4 v[32:33], v[12:15], off offset:2048
	s_nop 0
	v_pk_mul_f32 v[16:17], v[24:25], v[34:35] op_sel_hi:[1,0]
	v_pk_mul_f32 v[18:19], v[26:27], v[34:35] op_sel_hi:[1,0]
	v_pk_mul_f32 v[12:13], v[16:17], v[62:63]
	v_pk_mul_f32 v[14:15], v[18:19], v[64:65]
	global_store_dwordx4 v[32:33], v[12:15], off offset:3072
	s_cbranch_scc0 .LBB0_77

; __device__ __forceinline__ int launder(int x) { asm volatile("" : "+v"(x)); return x; }
; __device__ __forceinline__ void ssd_conv_tile(const Params& p, int l, int tile, unsigned char* smem) {
;   const int b = tile >> 7, t34 = tile & 127, pp0 = t34 * 34;
;   const size_t r0 = (size_t)b * TPB + pp0;
;   bf16_t* T = (bf16_t*)smem;
;   const int tid = launder(threadIdx.x);
;   for (int q = tid; q < 34 * 112; q += 256) {
;     const int rr = q / 112, cc = q % 112;
;     *(uint4*)(T + (rr + 1) * 896 + cc * 8) = *(const uint4*)(p.PS + (r0 + rr) * 912 + cc * 8);
;   }
.LBB0_802:
	s_and_b64 vcc, exec, s[42:43]
	s_cbranch_vccz .LBB0_830
	s_add_i32 s61, s47, 0xfffffbc0
	s_lshr_b32 s28, s61, 7
	s_and_b32 s58, s61, 0x7f
	s_mul_i32 s60, s58, 34
	s_mulk_i32 s28, 0x1100
	s_nop 0
	v_mov_b32_e32 v33, v189
	s_movk_i32 s42, 0xee0
	s_add_i32 s28, s28, s60
	s_nop 0
	v_cmp_gt_i32_e32 vcc, s42, v33
	s_and_saveexec_b64 s[42:43], vcc
	v_readlane_b32 s0, v251, 48
	v_readlane_b32 s14, v251, 62
	v_readlane_b32 s15, v251, 63
	s_mov_b32 s0, 0x92492493
	v_readlane_b32 s1, v251, 49
	v_readlane_b32 s2, v251, 50
	v_readlane_b32 s3, v251, 51
	v_readlane_b32 s4, v251, 52
	v_readlane_b32 s5, v251, 53
	v_readlane_b32 s6, v251, 54
	v_readlane_b32 s7, v251, 55
	v_readlane_b32 s8, v251, 56
	v_readlane_b32 s9, v251, 57
	v_readlane_b32 s10, v251, 58
	v_readlane_b32 s11, v251, 59
	v_readlane_b32 s12, v251, 60
	v_readlane_b32 s13, v251, 61
	s_cbranch_execz .LBB0_806
	v_readlane_b32 s4, v255, 29
	s_mov_b32 s1, 0x2492493
	s_movk_i32 s2, 0x720
	s_movk_i32 s3, 0xe0
	v_lshl_add_u32 v124, v33, 4, s4
	v_mul_hi_u32 v121, v33, s1
	v_mul_u32_u24_e32 v122, 0x70, v121
	v_sub_u32_e32 v122, v33, v122
	v_add_u32_e32 v121, s28, v121
	v_mul_u32_u24_e32 v121, s2, v121
	v_lshl_add_u32 v121, v122, 4, v121
	global_load_dwordx4 v[60:63], v121, s[14:15]
	v_add_u32_e32 v120, 0x100, v33
	v_mul_hi_u32 v121, v120, s1
	v_mul_u32_u24_e32 v122, 0x70, v121
	v_sub_u32_e32 v122, v120, v122
	v_add_u32_e32 v121, s28, v121
	v_mul_u32_u24_e32 v121, s2, v121
	v_lshl_add_u32 v121, v122, 4, v121
	global_load_dwordx4 v[64:67], v121, s[14:15]
	v_add_u32_e32 v120, 0x200, v33
	v_mul_hi_u32 v121, v120, s1
	v_mul_u32_u24_e32 v122, 0x70, v121
	v_sub_u32_e32 v122, v120, v122
	v_add_u32_e32 v121, s28, v121
	v_mul_u32_u24_e32 v121, s2, v121
	v_lshl_add_u32 v121, v122, 4, v121
	global_load_dwordx4 v[68:71], v121, s[14:15]
	v_add_u32_e32 v120, 0x300, v33
	v_mul_hi_u32 v121, v120, s1
	v_mul_u32_u24_e32 v122, 0x70, v121
	v_sub_u32_e32 v122, v120, v122
	v_add_u32_e32 v121, s28, v121
	v_mul_u32_u24_e32 v121, s2, v121
	v_lshl_add_u32 v121, v122, 4, v121
	global_load_dwordx4 v[72:75], v121, s[14:15]
	v_add_u32_e32 v120, 0x400, v33
	v_mul_hi_u32 v121, v120, s1
	v_mul_u32_u24_e32 v122, 0x70, v121
	v_sub_u32_e32 v122, v120, v122
	v_add_u32_e32 v121, s28, v121
	v_mul_u32_u24_e32 v121, s2, v121
	v_lshl_add_u32 v121, v122, 4, v121
	global_load_dwordx4 v[76:79], v121, s[14:15]
	v_add_u32_e32 v120, 0x500, v33
	v_mul_hi_u32 v121, v120, s1
	v_mul_u32_u24_e32 v122, 0x70, v121
	v_sub_u32_e32 v122, v120, v122
	v_add_u32_e32 v121, s28, v121
	v_mul_u32_u24_e32 v121, s2, v121
	v_lshl_add_u32 v121, v122, 4, v121
	global_load_dwordx4 v[80:83], v121, s[14:15]
	v_add_u32_e32 v120, 0x600, v33
	v_mul_hi_u32 v121, v120, s1
	v_mul_u32_u24_e32 v122, 0x70, v121
	v_sub_u32_e32 v122, v120, v122
	v_add_u32_e32 v121, s28, v121
	v_mul_u32_u24_e32 v121, s2, v121
	v_lshl_add_u32 v121, v122, 4, v121
	global_load_dwordx4 v[84:87], v121, s[14:15]
	v_add_u32_e32 v120, 0x700, v33
	v_mul_hi_u32 v121, v120, s1
	v_mul_u32_u24_e32 v122, 0x70, v121
	v_sub_u32_e32 v122, v120, v122
	v_add_u32_e32 v121, s28, v121
	v_mul_u32_u24_e32 v121, s2, v121
	v_lshl_add_u32 v121, v122, 4, v121
	global_load_dwordx4 v[88:91], v121, s[14:15]
	v_add_u32_e32 v120, 0x800, v33
	v_mul_hi_u32 v121, v120, s1
	v_mul_u32_u24_e32 v122, 0x70, v121
	v_sub_u32_e32 v122, v120, v122
	v_add_u32_e32 v121, s28, v121
	v_mul_u32_u24_e32 v121, s2, v121
	v_lshl_add_u32 v121, v122, 4, v121
	global_load_dwordx4 v[92:95], v121, s[14:15]
	v_add_u32_e32 v120, 0x900, v33
	v_mul_hi_u32 v121, v120, s1
	v_mul_u32_u24_e32 v122, 0x70, v121
	v_sub_u32_e32 v122, v120, v122
	v_add_u32_e32 v121, s28, v121
	v_mul_u32_u24_e32 v121, s2, v121
	v_lshl_add_u32 v121, v122, 4, v121
	global_load_dwordx4 v[96:99], v121, s[14:15]
	v_add_u32_e32 v120, 0xa00, v33
	v_mul_hi_u32 v121, v120, s1
	v_mul_u32_u24_e32 v122, 0x70, v121
	v_sub_u32_e32 v122, v120, v122
	v_add_u32_e32 v121, s28, v121
	v_mul_u32_u24_e32 v121, s2, v121
	v_lshl_add_u32 v121, v122, 4, v121
	global_load_dwordx4 v[100:103], v121, s[14:15]
	v_add_u32_e32 v120, 0xb00, v33
	v_mul_hi_u32 v121, v120, s1
	v_mul_u32_u24_e32 v122, 0x70, v121
	v_sub_u32_e32 v122, v120, v122
	v_add_u32_e32 v121, s28, v121
	v_mul_u32_u24_e32 v121, s2, v121
	v_lshl_add_u32 v121, v122, 4, v121
	global_load_dwordx4 v[104:107], v121, s[14:15]
	v_add_u32_e32 v120, 0xc00, v33
	v_mul_hi_u32 v121, v120, s1
	v_mul_u32_u24_e32 v122, 0x70, v121
	v_sub_u32_e32 v122, v120, v122
	v_add_u32_e32 v121, s28, v121
	v_mul_u32_u24_e32 v121, s2, v121
	v_lshl_add_u32 v121, v122, 4, v121
	global_load_dwordx4 v[108:111], v121, s[14:15]
	v_add_u32_e32 v120, 0xd00, v33
	v_mul_hi_u32 v121, v120, s1
	v_mul_u32_u24_e32 v122, 0x70, v121
	v_sub_u32_e32 v122, v120, v122
	v_add_u32_e32 v121, s28, v121
	v_mul_u32_u24_e32 v121, s2, v121
	v_lshl_add_u32 v121, v122, 4, v121
	global_load_dwordx4 v[112:115], v121, s[14:15]
	v_add_u32_e32 v120, 0xe00, v33
	v_mul_hi_u32 v121, v120, s1
	v_mul_u32_u24_e32 v122, 0x70, v121
	v_sub_u32_e32 v122, v120, v122
	v_add_u32_e32 v121, s28, v121
	v_mul_u32_u24_e32 v121, s2, v121
	v_lshl_add_u32 v121, v122, 4, v121
	v_cmp_gt_u32_e64 s[44:45], s3, v33
	s_and_saveexec_b64 s[56:57], s[44:45]
	global_load_dwordx4 v[116:119], v121, s[14:15]
	s_mov_b64 exec, s[56:57]

; __device__ __forceinline__ void phase_setup(const Params& p, unsigned char* smem) {
;     ...
;       const float* wp = p.ada_w + ((size_t)l * 1024 + kg * 128) * 3072 + n0 + col;
; #pragma unroll 8
;       for (int k = 0; k < 128; ++k) {
;         float w = wp[(size_t)k * 3072];
;         int kk = kg * 128 + k;
;         a0 += cact[kk] * w; a1 += cact[1024 + kk] * w; a2 += cact[2048 + kk] * w; a3 += cact[3072 + kk] * w; a4 += cact[4096 + kk] * w;
;       }
.LBB0_1364:
	v_lshl_add_u64 v[26:27], v[16:17], 0, s[58:59]
	s_waitcnt vmcnt(0)
	v_add_co_u32_e32 v28, vcc, s41, v26
	s_movk_i32 s60, 0x6000
	s_nop 0
	v_addc_co_u32_e32 v29, vcc, 0, v27, vcc
	v_add_co_u32_e32 v30, vcc, s60, v26
	s_mov_b32 s60, 0x9000
	s_nop 0
	v_addc_co_u32_e32 v31, vcc, 0, v27, vcc
	v_add_co_u32_e32 v32, vcc, s60, v26
	s_mov_b32 s60, 0xc000
	s_nop 0
	v_addc_co_u32_e32 v33, vcc, 0, v27, vcc
	global_load_dword v66, v[26:27], off
	v_add_co_u32_e32 v34, vcc, s60, v26
	s_mov_b32 s60, 0xf000
	s_nop 0
	v_addc_co_u32_e32 v35, vcc, 0, v27, vcc
	v_add_co_u32_e32 v36, vcc, s60, v26
	s_mov_b32 s60, 0x12000
	s_nop 0
	v_addc_co_u32_e32 v37, vcc, 0, v27, vcc
	v_add_co_u32_e32 v38, vcc, s60, v26
	s_mov_b32 s60, 0x15000
	s_nop 0
	v_addc_co_u32_e32 v39, vcc, 0, v27, vcc
	v_add_co_u32_e32 v26, vcc, s60, v26
	s_add_u32 s58, s58, 0x18000
	s_nop 0
	v_addc_co_u32_e32 v27, vcc, 0, v27, vcc
	global_load_dword v68, v[28:29], off
	global_load_dword v70, v[30:31], off
	global_load_dword v72, v[32:33], off
	global_load_dword v74, v[34:35], off
	global_load_dword v76, v[36:37], off
	global_load_dword v78, v[38:39], off
	global_load_dword v80, v[26:27], off
	v_lshl_add_u64 v[26:27], v[16:17], 0, s[58:59]
	v_add_co_u32_e32 v28, vcc, s41, v26
	s_movk_i32 s60, 0x6000
	s_nop 0
	v_addc_co_u32_e32 v29, vcc, 0, v27, vcc
	v_add_co_u32_e32 v30, vcc, s60, v26
	s_mov_b32 s60, 0x9000
	s_nop 0
	v_addc_co_u32_e32 v31, vcc, 0, v27, vcc
	v_add_co_u32_e32 v32, vcc, s60, v26
	s_mov_b32 s60, 0xc000
	s_nop 0
	v_addc_co_u32_e32 v33, vcc, 0, v27, vcc
	global_load_dword v86, v[26:27], off
	v_add_co_u32_e32 v34, vcc, s60, v26
	s_mov_b32 s60, 0xf000
	s_nop 0
	v_addc_co_u32_e32 v35, vcc, 0, v27, vcc
	v_add_co_u32_e32 v36, vcc, s60, v26
	s_mov_b32 s60, 0x12000
	s_nop 0
	v_addc_co_u32_e32 v37, vcc, 0, v27, vcc
	v_add_co_u32_e32 v38, vcc, s60, v26
	s_mov_b32 s60, 0x15000
	s_nop 0
	v_addc_co_u32_e32 v39, vcc, 0, v27, vcc
	v_add_co_u32_e32 v26, vcc, s60, v26
	s_add_u32 s58, s58, 0x18000
	s_nop 0
	v_addc_co_u32_e32 v27, vcc, 0, v27, vcc
	global_load_dword v88, v[28:29], off
	global_load_dword v90, v[30:31], off
	global_load_dword v92, v[32:33], off
	global_load_dword v94, v[34:35], off
	global_load_dword v96, v[36:37], off
	global_load_dword v98, v[38:39], off
	global_load_dword v100, v[26:27], off
	ds_read_b128 v[26:29], v15
	ds_read_b128 v[30:33], v15 offset:16
	ds_read_b128 v[34:37], v15 offset:4096
	ds_read_b128 v[38:41], v15 offset:4112
	ds_read_b128 v[42:45], v15 offset:8192
	ds_read_b128 v[46:49], v15 offset:8208
	ds_read_b128 v[50:53], v15 offset:12288
	ds_read_b128 v[54:57], v15 offset:12304
	ds_read_b128 v[58:61], v15 offset:16384
	ds_read_b128 v[62:65], v15 offset:16400
	s_waitcnt lgkmcnt(9)
	v_mov_b32_e32 v82, v26
	s_waitcnt lgkmcnt(7)
	v_mov_b32_e32 v83, v34
	s_waitcnt lgkmcnt(5)
	v_mov_b32_e32 v84, v42
	s_waitcnt lgkmcnt(3)
	v_mov_b32_e32 v85, v50
	v_mov_b32_e32 v34, v27
	v_mov_b32_e32 v50, v43
	v_mov_b32_e32 v26, v28
	v_mov_b32_e32 v27, v36
	v_mov_b32_e32 v42, v44
	v_mov_b32_e32 v43, v52
	v_mov_b32_e32 v36, v29
	v_mov_b32_e32 v52, v45
	v_mov_b32_e32 v28, v30
	v_mov_b32_e32 v29, v38
	v_mov_b32_e32 v44, v46
	s_waitcnt lgkmcnt(2)
	v_mov_b32_e32 v45, v54
	v_mov_b32_e32 v38, v31
	v_mov_b32_e32 v54, v47
	v_mov_b32_e32 v30, v32
	v_mov_b32_e32 v31, v40
	v_mov_b32_e32 v46, v48
	v_mov_b32_e32 v47, v56
	v_mov_b32_e32 v40, v33
	v_mov_b32_e32 v56, v49
	v_add_u32_e32 v15, 32, v15
	s_waitcnt vmcnt(15)
	v_pk_fma_f32 v[18:19], v[66:67], v[82:83], v[18:19] op_sel_hi:[0,1,1]
	v_pk_fma_f32 v[20:21], v[66:67], v[84:85], v[20:21] op_sel_hi:[0,1,1]
	s_waitcnt lgkmcnt(1)
	v_fmac_f32_e32 v1, v66, v58
	s_waitcnt vmcnt(14)
	v_pk_fma_f32 v[18:19], v[68:69], v[34:35], v[18:19] op_sel_hi:[0,1,1]
	v_pk_fma_f32 v[20:21], v[68:69], v[50:51], v[20:21] op_sel_hi:[0,1,1]
	v_fmac_f32_e32 v1, v68, v59
	s_waitcnt vmcnt(13)
	v_pk_fma_f32 v[18:19], v[70:71], v[26:27], v[18:19] op_sel_hi:[0,1,1]
	v_pk_fma_f32 v[20:21], v[70:71], v[42:43], v[20:21] op_sel_hi:[0,1,1]
	v_fmac_f32_e32 v1, v70, v60
	s_waitcnt vmcnt(12)
	v_pk_fma_f32 v[18:19], v[72:73], v[36:37], v[18:19] op_sel_hi:[0,1,1]
	v_pk_fma_f32 v[20:21], v[72:73], v[52:53], v[20:21] op_sel_hi:[0,1,1]
	v_fmac_f32_e32 v1, v72, v61
	s_waitcnt vmcnt(11)
	v_pk_fma_f32 v[18:19], v[74:75], v[28:29], v[18:19] op_sel_hi:[0,1,1]
	v_pk_fma_f32 v[20:21], v[74:75], v[44:45], v[20:21] op_sel_hi:[0,1,1]
	s_waitcnt lgkmcnt(0)
	v_fmac_f32_e32 v1, v74, v62
	s_waitcnt vmcnt(10)
	v_pk_fma_f32 v[18:19], v[76:77], v[38:39], v[18:19] op_sel_hi:[0,1,1]
	v_pk_fma_f32 v[20:21], v[76:77], v[54:55], v[20:21] op_sel_hi:[0,1,1]
	v_fmac_f32_e32 v1, v76, v63
	s_waitcnt vmcnt(9)
	v_pk_fma_f32 v[18:19], v[78:79], v[30:31], v[18:19] op_sel_hi:[0,1,1]
	v_pk_fma_f32 v[20:21], v[78:79], v[46:47], v[20:21] op_sel_hi:[0,1,1]
	v_fmac_f32_e32 v1, v78, v64
	s_waitcnt vmcnt(8)
; __device__ __forceinline__ void phase_setup(const Params& p, unsigned char* smem) {
;     ...
;       for (int k = 0; k < 128; ++k) {
;         float w = wp[(size_t)k * 3072];
;         int kk = kg * 128 + k;
;         a0 += cact[kk] * w; a1 += cact[1024 + kk] * w; a2 += cact[2048 + kk] * w; a3 += cact[3072 + kk] * w; a4 += cact[4096 + kk] * w;
;       }
;       float* red = cact + 5120;
;       red[(kg * 5 + 0) * 32 + col] = a0; red[(kg * 5 + 1) * 32 + col] = a1; red[(kg * 5 + 2) * 32 + col] = a2;
;       red[(kg * 5 + 3) * 32 + col] = a3; red[(kg * 5 + 4) * 32 + col] = a4;
;       __syncthreads();
;       if (tid < 160) {
;         int j = tid >> 5, cc = tid & 31;
;         float s = 0;
; #pragma unroll
;         for (int g = 0; g < 8; ++g) s += red[(g * 5 + j) * 32 + cc];
;         p.mod[(size_t)(l * 5 + j) * 3072 + n0 + cc] = s + p.ada_b[l * 3072 + n0 + cc];
;       }
	v_pk_fma_f32 v[18:19], v[80:81], v[40:41], v[18:19] op_sel_hi:[0,1,1]
	v_pk_fma_f32 v[20:21], v[80:81], v[56:57], v[20:21] op_sel_hi:[0,1,1]
	v_fmac_f32_e32 v1, v80, v65
	ds_read_b128 v[26:29], v15
	ds_read_b128 v[30:33], v15 offset:16
	ds_read_b128 v[34:37], v15 offset:4096
	ds_read_b128 v[38:41], v15 offset:4112
	ds_read_b128 v[42:45], v15 offset:8192
	ds_read_b128 v[46:49], v15 offset:8208
	ds_read_b128 v[50:53], v15 offset:12288
	ds_read_b128 v[54:57], v15 offset:12304
	ds_read_b128 v[58:61], v15 offset:16384
	ds_read_b128 v[62:65], v15 offset:16400
	s_waitcnt lgkmcnt(9)
	v_mov_b32_e32 v82, v26
	s_waitcnt lgkmcnt(7)
	v_mov_b32_e32 v83, v34
	s_waitcnt lgkmcnt(5)
	v_mov_b32_e32 v84, v42
	s_waitcnt lgkmcnt(3)
	v_mov_b32_e32 v85, v50
	v_mov_b32_e32 v34, v27
	v_mov_b32_e32 v50, v43
	v_mov_b32_e32 v26, v28
	v_mov_b32_e32 v27, v36
	v_mov_b32_e32 v42, v44
	v_mov_b32_e32 v43, v52
	v_mov_b32_e32 v36, v29
	v_mov_b32_e32 v52, v45
	v_mov_b32_e32 v28, v30
	v_mov_b32_e32 v29, v38
	v_mov_b32_e32 v44, v46
	s_waitcnt lgkmcnt(2)
	v_mov_b32_e32 v45, v54
	v_mov_b32_e32 v38, v31
	v_mov_b32_e32 v54, v47
	v_mov_b32_e32 v30, v32
	v_mov_b32_e32 v31, v40
	v_mov_b32_e32 v46, v48
	v_mov_b32_e32 v47, v56
	v_mov_b32_e32 v40, v33
	v_mov_b32_e32 v56, v49
	v_add_u32_e32 v15, 32, v15
	s_cmp_eq_u32 s58, 0x180000
	s_waitcnt vmcnt(7)
	v_pk_fma_f32 v[18:19], v[86:87], v[82:83], v[18:19] op_sel_hi:[0,1,1]
	v_pk_fma_f32 v[20:21], v[86:87], v[84:85], v[20:21] op_sel_hi:[0,1,1]
	s_waitcnt lgkmcnt(1)
	v_fmac_f32_e32 v1, v86, v58
	s_waitcnt vmcnt(6)
	v_pk_fma_f32 v[18:19], v[88:89], v[34:35], v[18:19] op_sel_hi:[0,1,1]
	v_pk_fma_f32 v[20:21], v[88:89], v[50:51], v[20:21] op_sel_hi:[0,1,1]
	v_fmac_f32_e32 v1, v88, v59
	s_waitcnt vmcnt(5)
	v_pk_fma_f32 v[18:19], v[90:91], v[26:27], v[18:19] op_sel_hi:[0,1,1]
	v_pk_fma_f32 v[20:21], v[90:91], v[42:43], v[20:21] op_sel_hi:[0,1,1]
	v_fmac_f32_e32 v1, v90, v60
	s_waitcnt vmcnt(4)
	v_pk_fma_f32 v[18:19], v[92:93], v[36:37], v[18:19] op_sel_hi:[0,1,1]
	v_pk_fma_f32 v[20:21], v[92:93], v[52:53], v[20:21] op_sel_hi:[0,1,1]
	v_fmac_f32_e32 v1, v92, v61
	s_waitcnt vmcnt(3)
	v_pk_fma_f32 v[18:19], v[94:95], v[28:29], v[18:19] op_sel_hi:[0,1,1]
	v_pk_fma_f32 v[20:21], v[94:95], v[44:45], v[20:21] op_sel_hi:[0,1,1]
	s_waitcnt lgkmcnt(0)
	v_fmac_f32_e32 v1, v94, v62
	s_waitcnt vmcnt(2)
	v_pk_fma_f32 v[18:19], v[96:97], v[38:39], v[18:19] op_sel_hi:[0,1,1]
	v_pk_fma_f32 v[20:21], v[96:97], v[54:55], v[20:21] op_sel_hi:[0,1,1]
	v_fmac_f32_e32 v1, v96, v63
	s_waitcnt vmcnt(1)
	v_pk_fma_f32 v[18:19], v[98:99], v[30:31], v[18:19] op_sel_hi:[0,1,1]
	v_pk_fma_f32 v[20:21], v[98:99], v[46:47], v[20:21] op_sel_hi:[0,1,1]
	v_fmac_f32_e32 v1, v98, v64
	s_waitcnt vmcnt(0)
	v_pk_fma_f32 v[18:19], v[100:101], v[40:41], v[18:19] op_sel_hi:[0,1,1]
	v_pk_fma_f32 v[20:21], v[100:101], v[56:57], v[20:21] op_sel_hi:[0,1,1]
	v_fmac_f32_e32 v1, v100, v65
	s_cbranch_scc0 .LBB0_1364
	v_add_u32_e32 v15, 0x5000, v8
	ds_write2_b32 v15, v18, v19 offset1:32
	ds_write2_b32 v15, v20, v21 offset0:64 offset1:96
	ds_write_b32 v8, v1 offset:20992
	s_waitcnt lgkmcnt(0)
	s_barrier
	s_and_saveexec_b64 s[58:59], s[48:49]
	s_cbranch_execz .LBB0_1367
	s_and_b64 s[60:61], s[56:57], exec
	s_cselect_b32 s60, 0xc00, 0
	s_add_i32 s60, s28, s60
	v_readlane_b32 s68, v253, 36
	v_or_b32_e32 v16, s60, v2
	v_mov_b32_e32 v17, v164
	v_readlane_b32 s78, v253, 46
	v_readlane_b32 s79, v253, 47
	v_add_u32_e32 v18, v6, v4
	v_add_u32_e32 v19, 0x5000, v18
	v_lshl_add_u64 v[16:17], v[16:17], 2, s[78:79]
	global_load_dword v1, v[16:17], off
	v_add_u32_e32 v20, 0x5400, v18
	v_add_u32_e32 v26, 0x5a00, v18
	v_add_u32_e32 v28, 0x5e00, v18
	ds_read2_b32 v[18:19], v19 offset1:160
	ds_read2_b32 v[20:21], v20 offset0:64 offset1:224
	ds_read2_b32 v[26:27], v26 offset1:160
	ds_read2_b32 v[28:29], v28 offset0:64 offset1:224
	v_readlane_b32 s0, v251, 48
	s_waitcnt lgkmcnt(3)
	v_add_f32_e32 v18, 0, v18
	v_add_f32_e32 v18, v18, v19
	s_waitcnt lgkmcnt(2)
	v_add_f32_e32 v18, v18, v20
	s_and_b64 s[56:57], s[56:57], exec
	v_add_f32_e32 v18, v18, v21
	v_readlane_b32 s2, v251, 50
	v_readlane_b32 s3, v251, 51
	s_cselect_b32 s56, 5, 0
	s_waitcnt lgkmcnt(1)
	v_add_f32_e32 v18, v18, v26
	v_mov_b64_e32 v[16:17], s[2:3]
	v_add_u32_e32 v30, s56, v3
	v_add_f32_e32 v18, v18, v27
	v_mad_i64_i32 v[16:17], s[56:57], v30, s41, v[16:17]
	s_waitcnt lgkmcnt(0)
	v_add_f32_e32 v18, v18, v28
	v_mov_b32_e32 v15, v164
	v_lshl_add_u64 v[16:17], s[28:29], 2, v[16:17]
	v_add_f32_e32 v18, v18, v29
	v_lshl_add_u64 v[14:15], v[16:17], 0, v[14:15]
	v_readlane_b32 s69, v253, 37
	v_readlane_b32 s70, v253, 38
	v_readlane_b32 s71, v253, 39
	v_readlane_b32 s72, v253, 40
	v_readlane_b32 s73, v253, 41
	v_readlane_b32 s74, v253, 42
	v_readlane_b32 s75, v253, 43
	v_readlane_b32 s76, v253, 44
	v_readlane_b32 s77, v253, 45
	v_readlane_b32 s80, v253, 48
	v_readlane_b32 s81, v253, 49
	v_readlane_b32 s82, v253, 50
	v_readlane_b32 s83, v253, 51
	v_readlane_b32 s1, v251, 49
	v_readlane_b32 s4, v251, 52
	v_readlane_b32 s5, v251, 53
	v_readlane_b32 s6, v251, 54
	v_readlane_b32 s7, v251, 55
	v_readlane_b32 s8, v251, 56
	v_readlane_b32 s9, v251, 57
	v_readlane_b32 s10, v251, 58
	v_readlane_b32 s11, v251, 59
	v_readlane_b32 s12, v251, 60
	v_readlane_b32 s13, v251, 61
	v_readlane_b32 s14, v251, 62
	v_readlane_b32 s15, v251, 63
	s_waitcnt vmcnt(0)
	v_add_f32_e32 v1, v18, v1
	global_store_dword v[14:15], v1, off
